# v9 plus PV blocks interleave one V-fragment read per MFMA (4 reads in flight) instead of 4-read bursts
# speedup vs baseline: 1.0054x; 1.0054x over previous
; #define ATT_WAITBAR(N) asm volatile("s_waitcnt vmcnt(" #N ") lgkmcnt(0)\n\ts_barrier" ::: "memory")
; #define ATT_PV(slot) do { bf16x8 va[4], vb[4]; ATT_LDV(va, slot, 0); ATT_SB; ATT_LDV(vb, slot, 1); ATT_SB; ATT_MMV(va, 0); ATT_SB; ATT_LDV(va, slot, 2); ATT_SB; ATT_MMV(vb, 1); ATT_SB; \
;         ATT_LDV(vb, slot, 3); ATT_SB; ATT_MMV(va, 2); ATT_SB; ATT_MMV(vb, 3); ATT_SB; } while (0)
; template <bool NOSHIFT> __device__ __forceinline__ void diff_attn_unit(LAS unsigned char* lds, bf16_t* proj, const bf16_t* VT, int b, int h, int qb, const AttnConsts ac, const float* gsub, const int tid, bf16_t* obuf, int opitch, int ocol) {
;     ...
;     ATT_ISSUE(0); ATT_ISSUE(1);
;     ATT_WAITBAR(4);
;     for (int t = 0; t < NT; ++t) {
;         const int bo = (t & 3) * 16384, sl_cur = bo, sl_prev = ((t - 1) & 3) * 16384;
;         if (t + 2 < NT) ATT_ISSUE(t + 2);
;         const int kv0 = 64 * t;
;         if (c == 1 && t >= 1 && kv0 - 64 <= qmax) ATT_PV(sl_prev);
.LBB1_287:
.LBB1_288:
	s_cmp_gt_u32 s47, s83
	s_cselect_b64 s[80:81], -1, 0
	s_or_b64 s[80:81], s[76:77], s[80:81]
	s_and_b64 vcc, exec, s[80:81]
	s_cbranch_vccnz .LBB1_290
	s_add_i32 s15, s14, 0x10000
	s_and_b32 s15, s15, 0xc000
	v_add_u32_e32 v7, s15, v193
	ds_read_b128 v[8:11], v7
	ds_read_b128 v[12:15], v7 offset:4096
	ds_read_b128 v[112:115], v7 offset:8192
	ds_read_b128 v[116:119], v7 offset:12288
	v_add_u32_e32 v224, s15, v204
	s_setprio 1
	ds_read_b128 v[120:123], v224
	s_waitcnt lgkmcnt(4)
	v_mfma_f32_32x32x16_bf16 v[80:95], v[8:11], v[104:107], v[80:95]
	ds_read_b128 v[124:127], v224 offset:4096
	s_waitcnt lgkmcnt(4)
	v_mfma_f32_32x32x16_bf16 v[64:79], v[12:15], v[104:107], v[64:79]
	ds_read_b128 v[128:131], v224 offset:8192
	s_waitcnt lgkmcnt(4)
	v_mfma_f32_32x32x16_bf16 v[48:63], v[112:115], v[104:107], v[48:63]
	ds_read_b128 v[132:135], v224 offset:12288
	s_waitcnt lgkmcnt(4)
	v_mfma_f32_32x32x16_bf16 v[32:47], v[116:119], v[104:107], v[32:47]
	v_add_u32_e32 v7, s15, v205
	ds_read_b128 v[8:11], v7
	s_waitcnt lgkmcnt(4)
	v_mfma_f32_32x32x16_bf16 v[80:95], v[120:123], v[100:103], v[80:95]
	ds_read_b128 v[12:15], v7 offset:4096
	s_waitcnt lgkmcnt(4)
	v_mfma_f32_32x32x16_bf16 v[64:79], v[124:127], v[100:103], v[64:79]
	ds_read_b128 v[112:115], v7 offset:8192
	s_waitcnt lgkmcnt(4)
	v_mfma_f32_32x32x16_bf16 v[48:63], v[128:131], v[100:103], v[48:63]
	ds_read_b128 v[116:119], v7 offset:12288
	s_waitcnt lgkmcnt(4)
	v_mfma_f32_32x32x16_bf16 v[32:47], v[132:135], v[100:103], v[32:47]
	v_add_u32_e32 v224, s15, v206
	ds_read_b128 v[120:123], v224
	s_waitcnt lgkmcnt(4)
	v_mfma_f32_32x32x16_bf16 v[80:95], v[8:11], v[96:99], v[80:95]
	ds_read_b128 v[124:127], v224 offset:4096
	s_waitcnt lgkmcnt(4)
	v_mfma_f32_32x32x16_bf16 v[64:79], v[12:15], v[96:99], v[64:79]
	ds_read_b128 v[128:131], v224 offset:8192
	s_waitcnt lgkmcnt(4)
	v_mfma_f32_32x32x16_bf16 v[48:63], v[112:115], v[96:99], v[48:63]
	ds_read_b128 v[132:135], v224 offset:12288
	s_waitcnt lgkmcnt(4)
	v_mfma_f32_32x32x16_bf16 v[32:47], v[116:119], v[96:99], v[32:47]
	s_waitcnt lgkmcnt(3)
	v_mfma_f32_32x32x16_bf16 v[80:95], v[120:123], v[108:111], v[80:95]
	s_waitcnt lgkmcnt(2)
	v_mfma_f32_32x32x16_bf16 v[64:79], v[124:127], v[108:111], v[64:79]
	s_waitcnt lgkmcnt(1)
	v_mfma_f32_32x32x16_bf16 v[48:63], v[128:131], v[108:111], v[48:63]
	s_waitcnt lgkmcnt(0)
	v_mfma_f32_32x32x16_bf16 v[32:47], v[132:135], v[108:111], v[32:47]
	s_setprio 0

; __device__ __forceinline__ unsigned pk2(float lo, float hi) { f32x2 v = {lo, hi}; bf16x2_t b = __builtin_convertvector(v, bf16x2_t); return __builtin_bit_cast(unsigned, b); }
; #define ATT_PV(slot) do { bf16x8 va[4], vb[4]; ATT_LDV(va, slot, 0); ATT_SB; ATT_LDV(vb, slot, 1); ATT_SB; ATT_MMV(va, 0); ATT_SB; ATT_LDV(va, slot, 2); ATT_SB; ATT_MMV(vb, 1); ATT_SB; \
;         ATT_LDV(vb, slot, 3); ATT_SB; ATT_MMV(va, 2); ATT_SB; ATT_MMV(vb, 3); ATT_SB; } while (0)
; template <bool NOSHIFT> __device__ __forceinline__ void diff_attn_unit(LAS unsigned char* lds, bf16_t* proj, const bf16_t* VT, int b, int h, int qb, const AttnConsts ac, const float* gsub, const int tid, bf16_t* obuf, int opitch, int ocol) {
;     ...
;             for (int kk = 0; kk < 4; ++kk) { const int mt = kk >> 1, r0 = 8 * (kk & 1); u32x4 w;
;                 w.x = pk2(p[mt][r0], p[mt][r0 + 1]); w.y = pk2(p[mt][r0 + 2], p[mt][r0 + 3]); w.z = pk2(p[mt][r0 + 4], p[mt][r0 + 5]); w.w = pk2(p[mt][r0 + 6], p[mt][r0 + 7]);
;                 pf[kk] = __builtin_bit_cast(bf16x8, w); }
;             if (c == 0) ATT_PV(sl_cur);
.Latt_cvt_done:
	s_andn2_b64 vcc, exec, s[72:73]
	s_cbranch_vccnz .LBB1_298
	v_add_u32_e32 v225, s15, v193
	ds_read_b128 v[8:11], v225
	ds_read_b128 v[12:15], v225 offset:4096
	ds_read_b128 v[112:115], v225 offset:8192
	ds_read_b128 v[116:119], v225 offset:12288
	v_add_u32_e32 v224, s15, v204
	s_setprio 1
	ds_read_b128 v[120:123], v224
	s_waitcnt lgkmcnt(4)
	v_mfma_f32_32x32x16_bf16 v[80:95], v[8:11], v[104:107], v[80:95]
	ds_read_b128 v[124:127], v224 offset:4096
	s_waitcnt lgkmcnt(4)
	v_mfma_f32_32x32x16_bf16 v[64:79], v[12:15], v[104:107], v[64:79]
	ds_read_b128 v[128:131], v224 offset:8192
	s_waitcnt lgkmcnt(4)
	v_mfma_f32_32x32x16_bf16 v[48:63], v[112:115], v[104:107], v[48:63]
	ds_read_b128 v[132:135], v224 offset:12288
	s_waitcnt lgkmcnt(4)
	v_mfma_f32_32x32x16_bf16 v[32:47], v[116:119], v[104:107], v[32:47]
	v_add_u32_e32 v225, s15, v205
	ds_read_b128 v[8:11], v225
	s_waitcnt lgkmcnt(4)
	v_mfma_f32_32x32x16_bf16 v[80:95], v[120:123], v[100:103], v[80:95]
	ds_read_b128 v[12:15], v225 offset:4096
	s_waitcnt lgkmcnt(4)
	v_mfma_f32_32x32x16_bf16 v[64:79], v[124:127], v[100:103], v[64:79]
	ds_read_b128 v[112:115], v225 offset:8192
	s_waitcnt lgkmcnt(4)
	v_mfma_f32_32x32x16_bf16 v[48:63], v[128:131], v[100:103], v[48:63]
	ds_read_b128 v[116:119], v225 offset:12288
	s_waitcnt lgkmcnt(4)
	v_mfma_f32_32x32x16_bf16 v[32:47], v[132:135], v[100:103], v[32:47]
	v_add_u32_e32 v224, s15, v206
	ds_read_b128 v[120:123], v224
	s_waitcnt lgkmcnt(4)
	v_mfma_f32_32x32x16_bf16 v[80:95], v[8:11], v[96:99], v[80:95]
	ds_read_b128 v[124:127], v224 offset:4096
	s_waitcnt lgkmcnt(4)
	v_mfma_f32_32x32x16_bf16 v[64:79], v[12:15], v[96:99], v[64:79]
	ds_read_b128 v[128:131], v224 offset:8192
	s_waitcnt lgkmcnt(4)
	v_mfma_f32_32x32x16_bf16 v[48:63], v[112:115], v[96:99], v[48:63]
	ds_read_b128 v[132:135], v224 offset:12288
	s_waitcnt lgkmcnt(4)
	v_mfma_f32_32x32x16_bf16 v[32:47], v[116:119], v[96:99], v[32:47]
	s_waitcnt lgkmcnt(3)
	v_mfma_f32_32x32x16_bf16 v[80:95], v[120:123], v[108:111], v[80:95]
	s_waitcnt lgkmcnt(2)
	v_mfma_f32_32x32x16_bf16 v[64:79], v[124:127], v[108:111], v[64:79]
	s_waitcnt lgkmcnt(1)
	v_mfma_f32_32x32x16_bf16 v[48:63], v[128:131], v[108:111], v[48:63]
	s_waitcnt lgkmcnt(0)
	v_mfma_f32_32x32x16_bf16 v[32:47], v[132:135], v[108:111], v[32:47]
	s_setprio 0
	s_branch .LBB1_298
